# GQA main loop head on a 2 KiB boundary (padding branched over)
# baseline (speedup 1.0000x reference)
.LBB0_706:
	s_mul_hi_i32 s0, s14, 0x2aaaaaab
	s_lshr_b32 s1, s0, 31
	s_ashr_i32 s0, s0, 5
	s_add_i32 s0, s0, s1
	s_mul_i32 s1, s0, 0xc0
	s_sub_i32 s1, s14, s1
	s_and_b32 s2, s1, 3
	s_bfe_u32 s4, s1, 0x10002
	s_mul_i32 s2, s2, 24
	s_ashr_i32 s1, s1, 3
	s_add_i32 s5, s2, s1
	s_bfe_i32 s2, s5, 0x80000
	s_bfe_u32 s2, s2, 0x5000a
	s_add_i32 s2, s5, s2
	s_bfe_i32 s2, s2, 0x80000
	s_mul_i32 s1, s4, 3
	s_bfe_u32 s2, s2, 0x80005
	s_add_i32 s6, s1, s2
	s_ashr_i32 s1, s0, 31
	s_lshl_b64 s[2:3], s[0:1], 13
	s_lshl_b32 s1, s5, 8
	s_and_b32 s1, s1, 0x1f00
	s_or_b32 s2, s2, s1
	s_mul_hi_u32 s5, s2, 0xe00
	s_mul_i32 s7, s3, 0xe00
	s_mul_i32 s1, s2, 0xe00
	s_add_i32 s5, s5, s7
	v_readlane_b32 s8, v254, 35
	v_readlane_b32 s9, v254, 36
	s_add_u32 s1, s8, s1
	s_addc_u32 s5, s9, s5
	s_lshl_b32 s16, s6, 6
	s_lshl_b32 s6, s6, 7
	s_add_u32 s1, s1, s6
	s_addc_u32 s5, s5, 0
	s_lshl_b32 s4, s4, 7
	s_add_u32 s6, s10, s4
	s_addc_u32 s7, s11, 0
	v_mov_b32_e32 v42, v191
	s_add_u32 s18, s12, s4
	s_addc_u32 s19, s13, 0
	v_readfirstlane_b32 s17, v42
	s_ashr_i32 s15, s17, 6
	s_lshl_b32 s8, s0, 8
	s_lshl_b32 s36, s15, 5
	s_lshl_b32 s9, s0, 13
	s_add_i32 s20, s8, 0x4000
	v_and_b32_e32 v189, 63, v42
	s_ashr_i32 s37, s36, 31
	s_mul_i32 s0, s15, 0x1c000
	s_mul_hi_i32 s4, s36, 0xe00
	s_add_u32 s22, s1, s0
	v_mul_u32_u24_e32 v0, 0x700, v189
	s_addc_u32 s23, s5, s4
	v_lshlrev_b32_e32 v0, 1, v0
	s_lshl_b32 s0, s15, 3
	v_lshl_add_u64 v[2:3], s[6:7], 0, v[0:1]
	s_ashr_i32 s1, s0, 31
	v_lshl_add_u64 v[192:193], s[0:1], 1, v[2:3]
	s_lshl_b32 s0, s15, 4
	v_bfe_u32 v0, v42, 2, 4
	v_and_or_b32 v0, s0, 48, v0
	v_mul_u32_u24_e32 v0, 0x700, v0
	s_ashr_i32 s0, s17, 3
	v_lshlrev_b32_e32 v0, 1, v0
	s_andn2_b32 s0, s0, 31
	v_lshl_add_u64 v[2:3], s[18:19], 0, v[0:1]
	s_ashr_i32 s1, s0, 31
	v_lshlrev_b32_e32 v198, 3, v42
	s_and_b32 s4, s17, 0x3fffffc0
	v_lshl_add_u64 v[2:3], s[0:1], 1, v[2:3]
	v_and_b32_e32 v201, 24, v198
	s_lshl_b32 s0, s15, 10
	v_lshlrev_b32_e32 v0, 1, v201
	s_cmp_lg_u32 0, -1
	v_lshl_add_u64 v[194:195], v[2:3], 0, v[0:1]
	s_cselect_b32 s1, 0, 0
	v_and_b32_e32 v199, 31, v42
	v_bfe_u32 v200, v42, 5, 1
	s_add_i32 s18, s0, s1
	v_mad_i64_i32 v[2:3], s[0:1], s9, v217, v[192:193]
	s_mov_b32 m0, s18
	s_nop 0
	global_load_lds_dwordx4 v[2:3], off
	s_add_i32 s19, s18, 0x6000
	v_mad_i64_i32 v[82:83], s[0:1], s9, v217, v[194:195]
	s_mov_b32 m0, s19
	s_nop 0
	global_load_lds_dwordx4 v[82:83], off
	s_or_b32 s1, s9, 64
	v_mul_u32_u24_e32 v0, 0x700, v199
	v_lshlrev_b32_e32 v203, 4, v200
	v_mad_i64_i32 v[2:3], s[6:7], s1, v217, v[192:193]
	s_add_i32 s0, s18, 0x2000
	s_mov_b32 m0, s0
	s_nop 0
	global_load_lds_dwordx4 v[2:3], off
	v_lshl_or_b32 v0, v0, 1, v203
	global_load_dwordx4 v[142:145], v0, s[22:23]
	global_load_dwordx4 v[138:141], v0, s[22:23] offset:32
	global_load_dwordx4 v[130:133], v0, s[22:23] offset:64
	global_load_dwordx4 v[122:125], v0, s[22:23] offset:96
	v_lshlrev_b32_e32 v2, 10, v200
	v_lshlrev_b32_e32 v3, 4, v199
	v_add3_u32 v206, 0, v2, v3
	v_mov_b32_e32 v2, v1
	v_mov_b32_e32 v3, v1
	v_mov_b32_e32 v4, v1
	v_mov_b32_e32 v5, v1
	v_mov_b32_e32 v6, v1
	v_mov_b32_e32 v7, v1
	v_mov_b32_e32 v8, v1
	v_mov_b32_e32 v9, v1
	v_mov_b32_e32 v10, v1
	v_mov_b32_e32 v11, v1
	v_mov_b32_e32 v12, v1
	v_mov_b32_e32 v13, v1
	v_mov_b32_e32 v14, v1
	v_mov_b32_e32 v15, v1
	v_mov_b32_e32 v0, v1
	v_mov_b64_e32 v[16:17], v[14:15]
	v_mov_b64_e32 v[14:15], v[12:13]
	v_mov_b64_e32 v[12:13], v[10:11]
	v_mov_b64_e32 v[10:11], v[8:9]
	v_mov_b64_e32 v[8:9], v[6:7]
	v_mov_b64_e32 v[6:7], v[4:5]
	v_mov_b64_e32 v[4:5], v[2:3]
	v_mov_b64_e32 v[2:3], v[0:1]
	s_or_b32 s0, s9, 0x80
	v_mad_i64_i32 v[18:19], s[6:7], s0, v217, v[192:193]
	s_add_i32 s0, s18, 0x4000
	s_mov_b32 m0, s0
	s_nop 0
	global_load_lds_dwordx4 v[18:19], off
	s_waitcnt vmcnt(3) lgkmcnt(0)
	s_barrier
	ds_read_b128 v[34:37], v206
	ds_read_b128 v[38:41], v206 offset:512
	s_waitcnt vmcnt(3) lgkmcnt(1)
	v_mfma_f32_32x32x16_bf16 v[18:33], v[34:37], v[142:145], v[2:17]
	v_lshlrev_b32_e32 v0, 1, v42
	v_and_b32_e32 v202, 32, v0
	v_lshlrev_b32_e32 v0, 4, v42
	s_lshl_b32 s4, s4, 2
	s_add_i32 s17, s4, 0
	s_or_b32 s4, s9, 0xc0
	v_and_b32_e32 v0, 0xc0, v0
	s_waitcnt lgkmcnt(0)
	v_mfma_f32_32x32x16_bf16 v[2:17], v[38:41], v[142:145], v[2:17]
	ds_read_b128 v[34:37], v206 offset:2048
	ds_read_b128 v[38:41], v206 offset:2560
	v_lshl_or_b32 v0, v200, 8, v0
	v_add_u32_e32 v84, 0, v202
	v_mov_b32_e32 v224, 0
	s_movk_i32 s21, 0x4000
	s_mov_b32 s23, -1
	s_mov_b32 s0, 0
	s_waitcnt vmcnt(2) lgkmcnt(1)
	v_mfma_f32_32x32x16_bf16 v[18:33], v[34:37], v[138:141], v[18:33]
	s_movk_i32 s24, 0x2000
	v_add3_u32 v207, v84, v201, v0
	v_cmp_gt_u32_e64 s[40:41], 32, v189
	v_lshl_add_u32 v204, v199, 2, s17
	v_lshl_add_u64 v[196:197], v[82:83], 0, s[28:29]
	s_waitcnt lgkmcnt(0)
	v_mfma_f32_32x32x16_bf16 v[2:17], v[38:41], v[138:141], v[2:17]
	ds_read_b128 v[34:37], v206 offset:4096
	ds_read_b128 v[38:41], v206 offset:4608
	s_waitcnt vmcnt(1) lgkmcnt(1)
	v_mfma_f32_32x32x16_bf16 v[18:33], v[34:37], v[130:133], v[18:33]
	s_waitcnt lgkmcnt(0)
	v_mfma_f32_32x32x16_bf16 v[2:17], v[38:41], v[130:133], v[2:17]
	ds_read_b128 v[34:37], v206 offset:6144
	ds_read_b128 v[38:41], v206 offset:6656
	s_waitcnt vmcnt(0) lgkmcnt(1)
	v_mfma_f32_32x32x16_bf16 v[18:33], v[34:37], v[122:125], v[18:33]
	s_waitcnt lgkmcnt(0)
	v_mfma_f32_32x32x16_bf16 v[2:17], v[38:41], v[122:125], v[2:17]
	s_nop 15
	s_nop 7
	s_nop 0
	v_max3_f32 v34, v18, v19, v2
	v_max3_f32 v35, v20, v21, v3
	s_nop 0
	v_max3_f32 v34, v34, v4, v5
	v_max3_f32 v35, v35, v24, v25
	s_nop 0
	v_max3_f32 v34, v34, v22, v23
	v_max3_f32 v35, v35, v8, v9
	s_nop 0
	v_max3_f32 v34, v34, v6, v7
	v_max3_f32 v35, v35, v28, v29
	s_nop 0
	v_max3_f32 v34, v34, v26, v27
	v_max3_f32 v35, v35, v12, v13
	s_nop 0
	v_max3_f32 v34, v34, v10, v11
	v_max3_f32 v35, v35, v32, v33
	s_nop 0
	v_max3_f32 v34, v34, v30, v31
	v_max3_f32 v35, v35, v16, v17
	s_nop 0
	v_max3_f32 v34, v34, v14, v15
	s_nop 0
	v_max_f32_e32 v34, v34, v35
	s_nop 0
	v_mov_b32_e32 v35, v34
	s_nop 1
	v_permlane32_swap_b32_e32 v34, v35
	v_max_f32_e32 v34, v34, v35
	s_nop 0
	v_add_f32_e32 v205, v1, v34
	v_sub_f32_e32 v18, v18, v34
	v_sub_f32_e32 v2, v2, v34
	v_sub_f32_e32 v19, v19, v34
	v_sub_f32_e32 v3, v3, v34
	v_sub_f32_e32 v20, v20, v34
	v_sub_f32_e32 v4, v4, v34
	v_sub_f32_e32 v21, v21, v34
	v_sub_f32_e32 v5, v5, v34
	v_sub_f32_e32 v22, v22, v34
	v_sub_f32_e32 v6, v6, v34
	v_sub_f32_e32 v23, v23, v34
	v_sub_f32_e32 v7, v7, v34
	v_sub_f32_e32 v24, v24, v34
	v_sub_f32_e32 v8, v8, v34
	v_sub_f32_e32 v25, v25, v34
	v_sub_f32_e32 v9, v9, v34
	v_sub_f32_e32 v26, v26, v34
	v_sub_f32_e32 v10, v10, v34
	v_sub_f32_e32 v27, v27, v34
	v_sub_f32_e32 v11, v11, v34
	v_sub_f32_e32 v28, v28, v34
	v_sub_f32_e32 v12, v12, v34
	v_sub_f32_e32 v29, v29, v34
	v_sub_f32_e32 v13, v13, v34
	v_sub_f32_e32 v30, v30, v34
	v_sub_f32_e32 v14, v14, v34
	v_sub_f32_e32 v31, v31, v34
	v_sub_f32_e32 v15, v15, v34
	v_sub_f32_e32 v32, v32, v34
	v_sub_f32_e32 v16, v16, v34
	v_sub_f32_e32 v33, v33, v34
	v_sub_f32_e32 v17, v17, v34
	s_nop 0
	v_xor_b32_e32 v34, 0x80000000, v205
	v_mov_b32_e32 v35, v34
	v_mov_b32_e32 v36, v34
	v_mov_b32_e32 v37, v34
	v_mov_b32_e32 v38, v34
	v_mov_b32_e32 v39, v34
	v_mov_b32_e32 v40, v34
	v_mov_b32_e32 v41, v34
	v_mov_b32_e32 v42, v34
	v_mov_b32_e32 v43, v34
	v_mov_b32_e32 v44, v34
	v_mov_b32_e32 v45, v34
	v_mov_b32_e32 v46, v34
	v_mov_b32_e32 v47, v34
	v_mov_b32_e32 v48, v34
	v_mov_b32_e32 v49, v34
	s_waitcnt vmcnt(0) lgkmcnt(0)
	s_barrier
	v_exp_f32_e32 v50, v2
	v_exp_f32_e32 v51, v3
	v_mad_i64_i32 v[2:3], s[4:5], s4, v217, v[192:193]
	s_mov_b32 m0, s18
	s_nop 0
	global_load_lds_dwordx4 v[2:3], off
	v_exp_f32_e32 v66, v18
	v_mad_i64_i32 v[2:3], s[4:5], s1, v217, v[194:195]
	s_add_i32 s1, s18, 0x8000
	s_mov_b32 m0, s1
	s_nop 0
	global_load_lds_dwordx4 v[2:3], off
	ds_read_b128 v[174:177], v206 offset:8192
	ds_read_b128 v[170:173], v206 offset:8704
	ds_read_b128 v[166:169], v206 offset:10240
	ds_read_b128 v[162:165], v206 offset:10752
	ds_read_b128 v[158:161], v206 offset:12288
	ds_read_b128 v[154:157], v206 offset:12800
	ds_read_b128 v[150:153], v206 offset:14336
	ds_read_b128 v[146:149], v206 offset:14848
	v_exp_f32_e32 v67, v19
	v_exp_f32_e32 v68, v20
	v_exp_f32_e32 v69, v21
	v_exp_f32_e32 v70, v22
	v_exp_f32_e32 v71, v23
	v_exp_f32_e32 v72, v24
	v_exp_f32_e32 v73, v25
	v_exp_f32_e32 v74, v26
	v_exp_f32_e32 v75, v27
	v_exp_f32_e32 v76, v28
	v_exp_f32_e32 v77, v29
	v_exp_f32_e32 v78, v30
	v_exp_f32_e32 v79, v31
	v_exp_f32_e32 v80, v32
	v_exp_f32_e32 v81, v33
	v_exp_f32_e32 v52, v4
	v_exp_f32_e32 v53, v5
	v_exp_f32_e32 v54, v6
	v_exp_f32_e32 v55, v7
	v_exp_f32_e32 v56, v8
	v_exp_f32_e32 v57, v9
	v_exp_f32_e32 v58, v10
	v_exp_f32_e32 v59, v11
	v_exp_f32_e32 v60, v12
	v_exp_f32_e32 v61, v13
	v_exp_f32_e32 v62, v14
	v_exp_f32_e32 v63, v15
	v_exp_f32_e32 v64, v16
	v_exp_f32_e32 v65, v17
	s_waitcnt vmcnt(2) lgkmcnt(0)
	s_barrier
	v_mov_b32_e32 v2, 0
	v_mov_b32_e32 v3, v224
	v_mov_b32_e32 v4, v224
	v_mov_b32_e32 v5, v224
	v_mov_b32_e32 v6, v224
	v_mov_b32_e32 v7, v224
	v_mov_b32_e32 v8, v224
	v_mov_b32_e32 v9, v224
	v_mov_b32_e32 v10, v224
	v_mov_b32_e32 v11, v224
	v_mov_b32_e32 v12, v224
	v_mov_b32_e32 v13, v224
	v_mov_b32_e32 v14, v224
	v_mov_b32_e32 v15, v224
	v_mov_b32_e32 v16, v224
	v_mov_b32_e32 v17, v224
	v_mov_b32_e32 v18, 0
	v_mov_b32_e32 v19, v224
	v_mov_b32_e32 v20, v224
	v_mov_b32_e32 v21, v224
	v_mov_b32_e32 v22, v224
	v_mov_b32_e32 v23, v224
	v_mov_b32_e32 v24, v224
	v_mov_b32_e32 v25, v224
	v_mov_b32_e32 v26, v224
	v_mov_b32_e32 v27, v224
	v_mov_b32_e32 v28, v224
	v_mov_b32_e32 v29, v224
	v_mov_b32_e32 v30, v224
	v_mov_b32_e32 v31, v224
	v_mov_b32_e32 v32, v224
	v_mov_b32_e32 v33, v224
	s_branch .LBB0_707
	.p2alignl 11, 3212836864
